# mixer C: dead per-wave K-tile address arithmetic removed from both prefetch blocks (about 58 instructions per unit), now that K comes from LDS
# baseline (speedup 1.0000x reference)
; __device__ __forceinline__ void c_prefetch(const bf16* P, int un, int tid, int wave, int fr, int fq, v4u (&vpre)[9], bf16x8& Q0, bf16x8& Q1, bf16x8 (&K)[8][2]) {
;     ...
;     const int r = rf + (wave >> 2), j = wave & 3;
;     int rs = r - 4; rs = rs < 0 ? 0 : rs; rs = rs > rows - 8 ? rows - 8 : rs;
;     const int kcol0 = j == 0 ? 0 : (j == 1 ? 8 : (j == 2 ? 24 : 32));
;     { const bf16* qp = P + (size_t)(s0 + r * 64 + 16 * j + fr) * DIN + C_QC + h * 64 + fq * 8; Q0 = *(const bf16x8*)qp; Q1 = *(const bf16x8*)(qp + 32); }
; #pragma unroll
;     for (int kt = 0; kt < 8; ++kt) { const bf16* kp = P + (size_t)(s0 + (rs + (kt >> 1)) * 64 + kcol0 + 16 * (kt & 1) + fr) * DIN + C_KC + h * 64 + fq * 8;
;         K[kt][0] = *(const bf16x8*)kp; K[kt][1] = *(const bf16x8*)(kp + 32); }
; __device__ __forceinline__ void mixC_mfma(const bf16* P, const float* rpb  , bf16* MIX, LAS unsigned char* lds, int bid, int G, int tid) {
;     ...
;     if (vb_ < NU) c_prefetch(P, vb_, tid, wave, fr, fq, vpre, Qn0, Qn1, Kn);
.LBB0_350:
	s_lshr_b32 s6, s8, 8
	s_add_i32 s12, s12, s6
	s_max_i32 s6, s12, 4
	s_add_i32 s6, s6, -4
	s_min_u32 s13, s6, s13
	s_lshl_b32 s6, s12, 6
	s_add_i32 s6, s6, s11
	s_lshl_b32 s7, s15, 4
	s_or_b32 s6, s6, s7
	v_or_b32_e32 v1, s6, v207
	v_mov_b64_e32 v[104:105], s[74:75]
	v_mad_i64_i32 v[38:39], s[6:7], v1, s9, v[104:105]
	v_lshl_add_u64 v[38:39], v[38:39], 0, s[4:5]
	v_lshlrev_b32_e32 v102, 4, v110
	v_lshl_add_u64 v[38:39], v[38:39], 0, v[102:103]
	s_mov_b64 s[6:7], 0x1a00
	s_lshl_b32 s11, s13, 6
	v_lshl_add_u64 v[42:43], v[38:39], 0, s[6:7]
	s_movk_i32 s6, 0x1000
	v_add_co_u32_e32 v38, vcc, s6, v38
	s_nop 1
	v_addc_co_u32_e32 v39, vcc, 0, v39, vcc
	s_mov_b64 s[6:7], 0x2000
	s_add_i32 s14, s11, 64
	s_add_i32 s14, s11, 0x80
	s_addk_i32 s11, 0xc0
	s_nop 0
	global_load_dwordx4 v[38:41], v[38:39], off offset:2560
	s_nop 0
	global_load_dwordx4 v[42:45], v[42:43], off offset:64
	s_nop 0
	s_nop 0
	s_nop 0
	s_nop 0
	s_nop 0
	s_nop 0
	s_nop 0
	s_nop 0
	s_nop 0
	s_nop 0
	s_nop 0
	s_nop 0
	s_nop 0
	s_nop 0
	s_nop 0
	s_nop 0
	s_nop 0
	s_nop 0
	s_nop 0
	s_nop 0
	s_nop 0
	s_nop 0
	s_nop 0
	s_nop 0
	s_nop 0
	s_nop 0
	s_nop 0
	s_nop 0
	s_nop 0
	s_nop 0
	s_nop 0
	s_andn2_b64 vcc, exec, s[0:1]
	s_cbranch_vccnz .LBB0_493

; __device__ __forceinline__ void c_prefetch(const bf16* P, int un, int tid, int wave, int fr, int fq, v4u (&vpre)[9], bf16x8& Q0, bf16x8& Q1, bf16x8 (&K)[8][2]) {
;     ...
;     const int r = rf + (wave >> 2), j = wave & 3;
;     int rs = r - 4; rs = rs < 0 ? 0 : rs; rs = rs > rows - 8 ? rows - 8 : rs;
;     const int kcol0 = j == 0 ? 0 : (j == 1 ? 8 : (j == 2 ? 24 : 32));
;     { const bf16* qp = P + (size_t)(s0 + r * 64 + 16 * j + fr) * DIN + C_QC + h * 64 + fq * 8; Q0 = *(const bf16x8*)qp; Q1 = *(const bf16x8*)(qp + 32); }
; #pragma unroll
;     for (int kt = 0; kt < 8; ++kt) { const bf16* kp = P + (size_t)(s0 + (rs + (kt >> 1)) * 64 + kcol0 + 16 * (kt & 1) + fr) * DIN + C_KC + h * 64 + fq * 8;
;         K[kt][0] = *(const bf16x8*)kp; K[kt][1] = *(const bf16x8*)(kp + 32); }
; __device__ __forceinline__ void mixC_mfma(const bf16* P, const float* rpb  , bf16* MIX, LAS unsigned char* lds, int bid, int G, int tid) {
;     ...
;         if (un + G < NU) c_prefetch(P, un + G, tid, wave, fr, fq, vpre, Qn0, Qn1, Kn);
.LBB0_491:
	s_add_i32 s27, s27, s12
	s_max_i32 s24, s27, 4
	s_add_i32 s24, s24, -4
	s_min_u32 s36, s24, s93
	s_lshl_b32 s24, s27, 6
	s_add_i32 s24, s24, s26
	v_or_b32_e32 v38, s24, v1
	v_mov_b64_e32 v[102:103], s[74:75]
	v_mad_i64_i32 v[38:39], s[24:25], v38, s79, v[102:103]
	v_lshl_add_u64 v[38:39], v[38:39], 0, s[84:85]
	s_lshl_b32 s26, s36, 6
	v_lshl_add_u64 v[38:39], v[38:39], 0, v[210:211]
	s_mov_b64 s[24:25], 0x1a00
	v_lshl_add_u64 v[42:43], v[38:39], 0, s[24:25]
	v_add_co_u32_e32 v38, vcc, 0x1000, v38
	s_nop 1
	v_addc_co_u32_e32 v39, vcc, 0, v39, vcc
	s_add_i32 s27, s26, 64
	s_add_i32 s27, s26, 0x80
	s_addk_i32 s26, 0xc0
	s_nop 0
	global_load_dwordx4 v[38:41], v[38:39], off offset:2560
	s_nop 0
	global_load_dwordx4 v[42:45], v[42:43], off offset:64
	s_nop 0
	s_nop 0
	s_nop 0
	s_nop 0
	s_nop 0
	s_nop 0
	s_nop 0
	s_nop 0
	s_nop 0
	s_nop 0
	s_nop 0
	s_nop 0
	s_nop 0
	s_nop 0
	s_nop 0
	s_nop 0
	s_nop 0
	s_nop 0
	s_nop 0
	s_nop 0
	s_nop 0
	s_nop 0
	s_nop 0
	s_nop 0
	s_nop 0
	s_nop 0
	s_nop 0
	s_nop 0
	s_nop 0
	s_nop 0
	s_nop 0
	v_mov_b32_e32 v138, 0xf149f2ca
	v_mov_b32_e32 v139, 0xf149f2ca
	s_and_saveexec_b64 s[84:85], s[0:1]
	s_cbranch_execz .LBB0_424

; __device__ __forceinline__ void c_prefetch(const bf16* P, int un, int tid, int wave, int fr, int fq, v4u (&vpre)[9], bf16x8& Q0, bf16x8& Q1, bf16x8 (&K)[8][2]) {
;     ...
;     const int r = rf + (wave >> 2), j = wave & 3;
;     int rs = r - 4; rs = rs < 0 ? 0 : rs; rs = rs > rows - 8 ? rows - 8 : rs;
;     const int kcol0 = j == 0 ? 0 : (j == 1 ? 8 : (j == 2 ? 24 : 32));
;     { const bf16* qp = P + (size_t)(s0 + r * 64 + 16 * j + fr) * DIN + C_QC + h * 64 + fq * 8; Q0 = *(const bf16x8*)qp; Q1 = *(const bf16x8*)(qp + 32); }
; #pragma unroll
;     for (int kt = 0; kt < 8; ++kt) { const bf16* kp = P + (size_t)(s0 + (rs + (kt >> 1)) * 64 + kcol0 + 16 * (kt & 1) + fr) * DIN + C_KC + h * 64 + fq * 8;
;         K[kt][0] = *(const bf16x8*)kp; K[kt][1] = *(const bf16x8*)(kp + 32); }
; __device__ __forceinline__ void mixC_mfma(const bf16* P, const float* rpb  , bf16* MIX, LAS unsigned char* lds, int bid, int G, int tid) {
;     ...
;     if (vb_ < NU) c_prefetch(P, vb_, tid, wave, fr, fq, vpre, Qn0, Qn1, Kn);
.LBB0_1375:
	s_lshr_b32 s6, s8, 8
	s_add_i32 s13, s13, s6
	s_max_i32 s6, s13, 4
	s_add_i32 s6, s6, -4
	s_min_u32 s14, s6, s14
	s_lshl_b32 s6, s13, 6
	s_add_i32 s6, s6, s11
	s_lshl_b32 s7, s16, 4
	s_or_b32 s6, s6, s7
	v_or_b32_e32 v1, s6, v213
	v_mov_b64_e32 v[104:105], s[74:75]
	v_mad_i64_i32 v[38:39], s[6:7], v1, s9, v[104:105]
	v_lshl_add_u64 v[38:39], v[38:39], 0, s[4:5]
	v_lshlrev_b32_e32 v102, 4, v110
	v_lshl_add_u64 v[38:39], v[38:39], 0, v[102:103]
	s_mov_b64 s[6:7], 0x1a00
	s_lshl_b32 s11, s14, 6
	v_lshl_add_u64 v[42:43], v[38:39], 0, s[6:7]
	s_movk_i32 s6, 0x1000
	v_add_co_u32_e32 v38, vcc, s6, v38
	s_nop 1
	v_addc_co_u32_e32 v39, vcc, 0, v39, vcc
	s_mov_b64 s[6:7], 0x2000
	s_add_i32 s13, s11, 64
	s_add_i32 s13, s11, 0x80
	s_addk_i32 s11, 0xc0
	s_nop 0
	global_load_dwordx4 v[38:41], v[38:39], off offset:2560
	s_nop 0
	global_load_dwordx4 v[42:45], v[42:43], off offset:64
	s_nop 0
	s_nop 0
	s_nop 0
	s_nop 0
	s_nop 0
	s_nop 0
	s_nop 0
	s_nop 0
	s_nop 0
	s_nop 0
	s_nop 0
	s_nop 0
	s_nop 0
	s_nop 0
	s_nop 0
	s_nop 0
	s_nop 0
	s_nop 0
	s_nop 0
	s_nop 0
	s_nop 0
	s_nop 0
	s_nop 0
	s_nop 0
	s_nop 0
	s_nop 0
	s_nop 0
	s_nop 0
	s_nop 0
	s_nop 0
	s_nop 0
	s_andn2_b64 vcc, exec, s[0:1]
	s_cbranch_vccnz .LBB0_1518

; __device__ __forceinline__ void c_prefetch(const bf16* P, int un, int tid, int wave, int fr, int fq, v4u (&vpre)[9], bf16x8& Q0, bf16x8& Q1, bf16x8 (&K)[8][2]) {
;     ...
;     const int r = rf + (wave >> 2), j = wave & 3;
;     int rs = r - 4; rs = rs < 0 ? 0 : rs; rs = rs > rows - 8 ? rows - 8 : rs;
;     const int kcol0 = j == 0 ? 0 : (j == 1 ? 8 : (j == 2 ? 24 : 32));
;     { const bf16* qp = P + (size_t)(s0 + r * 64 + 16 * j + fr) * DIN + C_QC + h * 64 + fq * 8; Q0 = *(const bf16x8*)qp; Q1 = *(const bf16x8*)(qp + 32); }
; #pragma unroll
;     for (int kt = 0; kt < 8; ++kt) { const bf16* kp = P + (size_t)(s0 + (rs + (kt >> 1)) * 64 + kcol0 + 16 * (kt & 1) + fr) * DIN + C_KC + h * 64 + fq * 8;
;         K[kt][0] = *(const bf16x8*)kp; K[kt][1] = *(const bf16x8*)(kp + 32); }
; __device__ __forceinline__ void mixC_mfma(const bf16* P, const float* rpb  , bf16* MIX, LAS unsigned char* lds, int bid, int G, int tid) {
;     ...
;         if (un + G < NU) c_prefetch(P, un + G, tid, wave, fr, fq, vpre, Qn0, Qn1, Kn);
.LBB0_1516:
	s_add_i32 s31, s31, s13
	s_max_i32 s43, s31, 4
	s_lshl_b32 s31, s31, 6
	s_add_i32 s43, s43, -4
	s_add_i32 s31, s31, s29
	s_min_u32 s35, s43, s35
	v_or_b32_e32 v38, s31, v1
	v_mov_b64_e32 v[102:103], s[74:75]
	v_mad_i64_i32 v[38:39], s[88:89], v38, s79, v[102:103]
	s_lshl_b32 s29, s35, 6
	v_lshl_add_u64 v[38:39], v[38:39], 0, s[40:41]
	v_lshl_add_u64 v[38:39], v[38:39], 0, v[210:211]
	v_lshl_add_u64 v[42:43], v[38:39], 0, s[22:23]
	v_add_co_u32_e32 v38, vcc, 0x1000, v38
	s_nop 1
	v_addc_co_u32_e32 v39, vcc, 0, v39, vcc
	s_add_i32 s31, s29, 64
	s_add_i32 s31, s29, 0x80
	s_addk_i32 s29, 0xc0
	s_nop 0
	global_load_dwordx4 v[38:41], v[38:39], off offset:2560
	s_nop 0
	global_load_dwordx4 v[42:45], v[42:43], off offset:64
	s_nop 0
	s_nop 0
	s_nop 0
	s_nop 0
	s_nop 0
	s_nop 0
	s_nop 0
	s_nop 0
	s_nop 0
	s_nop 0
	s_nop 0
	s_nop 0
	s_nop 0
	s_nop 0
	s_nop 0
	s_nop 0
	s_nop 0
	s_nop 0
	s_nop 0
	s_nop 0
	s_nop 0
	s_nop 0
	s_nop 0
	s_nop 0
	s_nop 0
	s_nop 0
	s_nop 0
	s_nop 0
	s_nop 0
	s_nop 0
	s_nop 0
	v_mov_b32_e32 v138, 0xf149f2ca
	v_mov_b32_e32 v139, 0xf149f2ca
	s_and_saveexec_b64 s[40:41], s[0:1]
	s_cbranch_execz .LBB0_1449
